# P3: odd workgroups run their scan fix-up chunk before their attention units (even ones after): the memory-bound fix-up of one half overlaps the attention of the other
# speedup vs baseline: 1.0044x; 1.0044x over previous
.LBB0_369:
	s_or_b64 exec, exec, s[40:41]
	v_readlane_b32 s4, v252, 6
	s_nop 0
	s_bitcmp1_b32 s4, 0
	s_cbranch_scc0 .Lp3_attn
	s_waitcnt lgkmcnt(0)
	s_barrier
	s_branch .Lp3_fix_entry
.Lp3_attn:
	v_readlane_b32 s4, v252, 62
	v_readlane_b32 s6, v254, 47
	v_readlane_b32 s5, v252, 63
	v_readlane_b32 s7, v254, 48
	s_lshl_b32 s12, s71, 6
	s_nor_b64 s[8:9], s[6:7], s[4:5]
	s_mov_b32 s26, 0
	s_lshl_b64 s[10:11], s[12:13], 2
	s_waitcnt lgkmcnt(0)
	s_barrier
	s_branch .LBB0_372

.LBB0_451:
	v_readlane_b32 s4, v252, 6
	s_nop 0
	s_bitcmp1_b32 s4, 0
	s_cbranch_scc1 .LBB0_557

.LBB0_555:
	v_lshl_add_u64 v[20:21], v[14:15], 0, s[4:5]
	global_load_dwordx4 v[16:19], v[20:21], off nt
	v_add_co_u32_e32 v22, vcc, 0x1100000, v20
	s_mov_b32 s6, 0xbe00000
	s_nop 0
	v_addc_co_u32_e32 v23, vcc, 0, v21, vcc
	global_load_dwordx4 v[22:25], v[22:23], off nt
	s_add_u32 s4, s4, 0x4000
	s_addc_u32 s5, s5, 0
	s_cmp_lg_u32 s4, 0x10000
	s_waitcnt vmcnt(1)
	v_lshlrev_b32_e32 v28, 16, v18
	v_lshlrev_b32_e32 v29, 16, v19
	v_and_b32_e32 v30, 0xffff0000, v18
	v_and_b32_e32 v31, 0xffff0000, v19
	v_lshl_add_u64 v[18:19], s[46:47], 0, v[12:13]
	v_add_co_u32_e32 v36, vcc, s6, v18
	v_lshlrev_b32_e32 v26, 16, v16
	s_nop 0
	v_addc_co_u32_e32 v37, vcc, 0, v19, vcc
	global_load_dwordx2 v[36:37], v[36:37], off offset:2048 nt
	v_lshlrev_b32_e32 v27, 16, v17
	v_and_b32_e32 v16, 0xffff0000, v16
	v_and_b32_e32 v17, 0xffff0000, v17
	s_waitcnt vmcnt(1)
	v_lshlrev_b32_e32 v32, 16, v22
	v_lshlrev_b32_e32 v33, 16, v23
	v_and_b32_e32 v22, 0xffff0000, v22
	v_and_b32_e32 v23, 0xffff0000, v23
	v_lshlrev_b32_e32 v34, 16, v24
	v_lshlrev_b32_e32 v35, 16, v25
	v_and_b32_e32 v24, 0xffff0000, v24
	v_and_b32_e32 v25, 0xffff0000, v25
	s_waitcnt lgkmcnt(1)
	v_pk_fma_f32 v[16:17], v[2:3], v[16:17], v[26:27]
	s_waitcnt lgkmcnt(0)
	v_pk_fma_f32 v[22:23], v[6:7], v[22:23], v[32:33]
	v_pk_fma_f32 v[26:27], v[4:5], v[30:31], v[28:29]
	v_pk_fma_f32 v[24:25], v[8:9], v[24:25], v[34:35]
	v_pk_add_f32 v[16:17], v[16:17], v[22:23]
	v_pk_add_f32 v[24:25], v[26:27], v[24:25]
	s_mov_b32 s6, 0x9c00000
	v_lshl_add_u64 v[12:13], v[12:13], 0, s[64:65]
	s_waitcnt vmcnt(0)
	v_lshlrev_b32_e32 v22, 16, v36
	v_and_b32_e32 v23, 0xffff0000, v36
	v_pk_mul_f32 v[26:27], v[22:23], v[22:23]
	s_nop 0
	v_fmamk_f32 v0, v26, 0xbdd2d3e7, v224
	v_mul_f32_e32 v0, v0, v22
	v_exp_f32_e32 v0, v0
	s_nop 0
	v_add_f32_e32 v0, 1.0, v0
	v_rcp_f32_e32 v26, v0
	v_fmamk_f32 v0, v27, 0xbdd2d3e7, v224
	v_mul_f32_e32 v0, v0, v23
	v_exp_f32_e32 v0, v0
	s_nop 0
	v_add_f32_e32 v0, 1.0, v0
	v_rcp_f32_e32 v27, v0
	s_nop 0
	v_pk_mul_f32 v[22:23], v[26:27], v[22:23]
	s_nop 0
	v_pk_mul_f32 v[16:17], v[22:23], v[16:17]
	s_nop 0
	v_cvt_pk_bf16_f32 v22, v16, v17
	v_lshlrev_b32_e32 v16, 16, v37
	v_and_b32_e32 v17, 0xffff0000, v37
	v_pk_mul_f32 v[26:27], v[16:17], v[16:17]
	s_nop 0
	v_fmamk_f32 v0, v26, 0xbdd2d3e7, v224
	v_mul_f32_e32 v0, v0, v16
	v_exp_f32_e32 v0, v0
	s_nop 0
	v_add_f32_e32 v0, 1.0, v0
	v_rcp_f32_e32 v26, v0
	v_fmamk_f32 v0, v27, 0xbdd2d3e7, v224
	v_mul_f32_e32 v0, v0, v17
	v_exp_f32_e32 v0, v0
	s_nop 0
	v_add_f32_e32 v0, 1.0, v0
	v_rcp_f32_e32 v27, v0
	s_nop 0
	v_pk_mul_f32 v[16:17], v[26:27], v[16:17]
	s_nop 0
	v_pk_mul_f32 v[16:17], v[16:17], v[24:25]
	s_nop 0
	v_cvt_pk_bf16_f32 v23, v16, v17
	v_lshl_add_u64 v[16:17], s[46:47], 0, v[10:11]
	v_add_co_u32_e32 v24, vcc, s6, v16
	s_mov_b32 s6, 0x1102000
	s_nop 0
	v_addc_co_u32_e32 v25, vcc, 0, v17, vcc
	global_store_dwordx2 v[24:25], v[22:23], off offset:1024
	v_add_co_u32_e32 v22, vcc, s3, v20
	v_lshl_add_u64 v[10:11], v[10:11], 0, s[62:63]
	s_nop 0
	v_addc_co_u32_e32 v23, vcc, 0, v21, vcc
	v_add_co_u32_e32 v20, vcc, s6, v20
	s_mov_b32 s6, 0xbe06000
	s_nop 0
	v_addc_co_u32_e32 v21, vcc, 0, v21, vcc
	global_load_dwordx4 v[24:27], v[22:23], off nt
	global_load_dwordx4 v[32:35], v[20:21], off nt
	v_add_co_u32_e32 v18, vcc, s6, v18
	s_mov_b32 s6, 0x9c04000
	s_nop 0
	v_addc_co_u32_e32 v19, vcc, 0, v19, vcc
	global_load_dwordx2 v[18:19], v[18:19], off offset:2048 nt
	v_add_co_u32_e32 v16, vcc, s6, v16
	s_waitcnt vmcnt(2)
	v_lshlrev_b32_e32 v20, 16, v24
	v_lshlrev_b32_e32 v21, 16, v25
	v_and_b32_e32 v24, 0xffff0000, v24
	v_and_b32_e32 v25, 0xffff0000, v25
	s_waitcnt vmcnt(1)
	v_lshlrev_b32_e32 v28, 16, v32
	v_lshlrev_b32_e32 v29, 16, v33
	v_and_b32_e32 v32, 0xffff0000, v32
	v_and_b32_e32 v33, 0xffff0000, v33
	v_lshlrev_b32_e32 v22, 16, v26
	v_lshlrev_b32_e32 v23, 16, v27
	v_and_b32_e32 v26, 0xffff0000, v26
	v_and_b32_e32 v27, 0xffff0000, v27
	v_lshlrev_b32_e32 v30, 16, v34
	v_lshlrev_b32_e32 v31, 16, v35
	v_and_b32_e32 v34, 0xffff0000, v34
	v_and_b32_e32 v35, 0xffff0000, v35
	v_pk_fma_f32 v[20:21], v[2:3], v[24:25], v[20:21]
	v_pk_fma_f32 v[24:25], v[6:7], v[32:33], v[28:29]
	v_pk_fma_f32 v[22:23], v[4:5], v[26:27], v[22:23]
	v_pk_fma_f32 v[26:27], v[8:9], v[34:35], v[30:31]
	v_pk_add_f32 v[20:21], v[20:21], v[24:25]
	s_waitcnt vmcnt(0)
	v_lshlrev_b32_e32 v24, 16, v18
	v_and_b32_e32 v25, 0xffff0000, v18
	v_pk_add_f32 v[22:23], v[22:23], v[26:27]
	v_pk_mul_f32 v[26:27], v[24:25], v[24:25]
	v_addc_co_u32_e32 v17, vcc, 0, v17, vcc
	v_fmamk_f32 v0, v26, 0xbdd2d3e7, v224
	v_mul_f32_e32 v0, v0, v24
	v_exp_f32_e32 v0, v0
	s_nop 0
	v_add_f32_e32 v0, 1.0, v0
	v_rcp_f32_e32 v26, v0
	v_fmamk_f32 v0, v27, 0xbdd2d3e7, v224
	v_mul_f32_e32 v0, v0, v25
	v_exp_f32_e32 v0, v0
	s_nop 0
	v_add_f32_e32 v0, 1.0, v0
	v_rcp_f32_e32 v27, v0
	s_nop 0
	v_pk_mul_f32 v[24:25], v[26:27], v[24:25]
	s_nop 0
	v_pk_mul_f32 v[20:21], v[24:25], v[20:21]
	s_nop 0
	v_cvt_pk_bf16_f32 v18, v20, v21
	v_lshlrev_b32_e32 v20, 16, v19
	v_and_b32_e32 v21, 0xffff0000, v19
	v_pk_mul_f32 v[24:25], v[20:21], v[20:21]
	s_nop 0
	v_fmamk_f32 v0, v24, 0xbdd2d3e7, v224
	v_mul_f32_e32 v0, v0, v20
	v_exp_f32_e32 v0, v0
	s_nop 0
	v_add_f32_e32 v0, 1.0, v0
	v_rcp_f32_e32 v24, v0
	v_fmamk_f32 v0, v25, 0xbdd2d3e7, v224
	v_mul_f32_e32 v0, v0, v21
	v_exp_f32_e32 v0, v0
	s_nop 0
	v_add_f32_e32 v0, 1.0, v0
	v_rcp_f32_e32 v25, v0
	s_nop 0
	v_pk_mul_f32 v[20:21], v[24:25], v[20:21]
	s_nop 0
	v_pk_mul_f32 v[20:21], v[20:21], v[22:23]
	s_nop 0
	v_cvt_pk_bf16_f32 v19, v20, v21
	global_store_dwordx2 v[16:17], v[18:19], off offset:1024
	s_cbranch_scc1 .LBB0_555
	s_add_i32 s18, s18, s42
	s_cmp_ge_i32 s18, s12
	s_barrier
	s_cbranch_scc0 .LBB0_452
	v_readlane_b32 s4, v252, 6
	s_nop 0
	s_bitcmp1_b32 s4, 0
	s_cbranch_scc1 .Lp3_attn
